# QKV and short-conv projection GEMM epilogues: per-row-block RMSNorm partial-sum loads issued together at epilogue start (no per-group load-wait round trips)
# speedup vs baseline: 1.0169x; 1.0078x over previous
.LBB0_1168:
	s_lshl_b32 s63, s94, 8
	s_add_i32 s63, s63, s52
	v_or_b32_e32 v134, s63, v1
	v_ashrrev_i32_e32 v135, 31, v134
	v_lshlrev_b64 v[130:131], 6, v[134:135]
	v_lshl_add_u64 v[130:131], v[160:161], 0, v[130:131]
	v_add_co_u32_e32 v224, vcc, 0x2000, v130
	s_nop 1
	v_addc_co_u32_e32 v225, vcc, 0, v131, vcc
	global_load_dwordx4 v[192:195], v[130:131], off offset:1024
	global_load_dwordx4 v[196:199], v[130:131], off offset:2048
	global_load_dwordx4 v[204:207], v[130:131], off offset:3072
	global_load_dwordx4 v[208:211], v[224:225], off
	global_load_dwordx4 v[212:215], v[224:225], off offset:1024
	global_load_dwordx4 v[216:219], v[224:225], off offset:2048
	global_load_dwordx4 v[220:223], v[224:225], off offset:3072
	global_load_dwordx4 v[130:133], v[130:131], off
	v_and_b32_e32 v137, 64, v188
	v_xor_b32_e32 v136, 16, v188
	v_add_u32_e32 v138, 64, v137
	v_cmp_lt_i32_e32 vcc, v136, v138
	s_waitcnt vmcnt(0)
	v_mov_b32_e32 v137, v132
	v_cndmask_b32_e32 v136, v188, v136, vcc
	v_lshlrev_b32_e32 v144, 2, v136
	v_mov_b32_e32 v136, v131
	v_mov_b32_e32 v131, v133
	v_pk_add_f32 v[130:131], v[136:137], v[130:131]
	v_xor_b32_e32 v132, 32, v188
	v_add_f32_e32 v130, v130, v131
	ds_bpermute_b32 v131, v144, v130
	v_cmp_lt_i32_e32 vcc, v132, v138
	v_mov_b64_e32 v[136:137], 0
	s_nop 0
	v_cndmask_b32_e32 v132, v188, v132, vcc
	v_lshlrev_b32_e32 v145, 2, v132
	s_waitcnt lgkmcnt(0)
	v_add_f32_e32 v132, v130, v131
	ds_bpermute_b32 v133, v145, v132
	v_cmp_lt_i32_e32 vcc, s19, v134
	v_mov_b64_e32 v[130:131], 0
	s_and_saveexec_b64 s[8:9], vcc
	s_cbranch_execz .LBB0_1177
	s_cmpk_gt_u32 s63, 0x43ff
	s_mov_b64 s[56:57], -1
	s_cbranch_scc0 .LBB0_1173
	s_cmpk_lt_u32 s63, 0x4480
	s_cselect_b64 s[22:23], -1, 0
	s_and_b64 s[22:23], s[22:23], s[0:1]
	v_mov_b64_e32 v[130:131], 0
	s_and_saveexec_b64 s[56:57], s[22:23]
	s_add_i32 s22, s63, 0xffffbc00
	s_lshr_b32 s22, s22, 4
	s_mulk_i32 s22, 0x63
	v_add_u32_e32 v136, s22, v182
	v_mov_b64_e32 v[130:131], s[20:21]
	v_mad_u64_u32 v[130:131], s[22:23], v136, s47, v[130:131]
	s_or_b64 exec, exec, s[56:57]
	s_mov_b64 s[56:57], 0

.LBB0_1185:
	s_or_b64 exec, exec, s[56:57]
	s_nop 0
	v_or_b32_e32 v114, 16, v134
	v_ashrrev_i32_e32 v115, 31, v114
	v_lshlrev_b64 v[116:117], 6, v[114:115]
	v_lshl_add_u64 v[116:117], v[160:161], 0, v[116:117]
	s_nop 1
	v_mov_b32_e32 v116, v192
	v_mov_b32_e32 v117, v193
	v_mov_b32_e32 v118, v194
	v_mov_b32_e32 v119, v195
	v_cmp_lt_i32_e32 vcc, s19, v114
	v_mov_b32_e32 v120, v117
	v_mov_b32_e32 v121, v118
	v_mov_b32_e32 v117, v119
	v_pk_add_f32 v[116:117], v[120:121], v[116:117]
	v_mov_b64_e32 v[120:121], 0
	v_add_f32_e32 v116, v116, v117
	ds_bpermute_b32 v117, v144, v116
	s_waitcnt lgkmcnt(0)
	v_add_f32_e32 v118, v116, v117
	ds_bpermute_b32 v119, v145, v118
	v_mov_b64_e32 v[116:117], 0
	s_and_saveexec_b64 s[8:9], vcc
	s_cbranch_execz .LBB0_1194
	s_cmpk_lt_u32 s63, 0x4400
	s_mov_b64 s[56:57], -1
	s_cbranch_scc1 .LBB0_1190
	s_cmpk_lt_u32 s63, 0x4480
	s_cselect_b64 s[22:23], -1, 0
	s_and_b64 s[22:23], s[22:23], s[0:1]
	v_mov_b64_e32 v[116:117], 0
	s_and_saveexec_b64 s[56:57], s[22:23]
	s_add_i32 s22, s63, 0xffffbc10
	s_lshr_b32 s22, s22, 4
	s_mulk_i32 s22, 0x63
	v_add_u32_e32 v120, s22, v182
	v_mov_b64_e32 v[116:117], s[20:21]
	v_mad_u64_u32 v[116:117], s[22:23], v120, s47, v[116:117]
	s_or_b64 exec, exec, s[56:57]
	s_mov_b64 s[56:57], 0

.LBB0_1202:
	s_or_b64 exec, exec, s[56:57]
	s_nop 0
	v_or_b32_e32 v98, 32, v134
	v_ashrrev_i32_e32 v99, 31, v98
	v_lshlrev_b64 v[100:101], 6, v[98:99]
	v_lshl_add_u64 v[100:101], v[160:161], 0, v[100:101]
	s_nop 1
	v_mov_b32_e32 v100, v196
	v_mov_b32_e32 v101, v197
	v_mov_b32_e32 v102, v198
	v_mov_b32_e32 v103, v199
	v_cmp_lt_i32_e32 vcc, s19, v98
	v_mov_b32_e32 v104, v101
	v_mov_b32_e32 v105, v102
	v_mov_b32_e32 v101, v103
	v_pk_add_f32 v[100:101], v[104:105], v[100:101]
	v_mov_b64_e32 v[104:105], 0
	v_add_f32_e32 v100, v100, v101
	ds_bpermute_b32 v101, v144, v100
	s_waitcnt lgkmcnt(0)
	v_add_f32_e32 v102, v100, v101
	ds_bpermute_b32 v103, v145, v102
	v_mov_b64_e32 v[100:101], 0
	s_and_saveexec_b64 s[8:9], vcc
	s_cbranch_execz .LBB0_1211
	s_cmpk_lt_u32 s63, 0x4400
	s_mov_b64 s[56:57], -1
	s_cbranch_scc1 .LBB0_1207
	s_cmpk_lt_u32 s63, 0x4480
	s_cselect_b64 s[22:23], -1, 0
	s_and_b64 s[22:23], s[22:23], s[0:1]
	v_mov_b64_e32 v[100:101], 0
	s_and_saveexec_b64 s[56:57], s[22:23]
	s_add_i32 s22, s63, 0xffffbc20
	s_lshr_b32 s22, s22, 4
	s_mulk_i32 s22, 0x63
	v_add_u32_e32 v104, s22, v182
	v_mov_b64_e32 v[100:101], s[20:21]
	v_mad_u64_u32 v[100:101], s[22:23], v104, s47, v[100:101]
	s_or_b64 exec, exec, s[56:57]
	s_mov_b64 s[56:57], 0

.LBB0_1219:
	s_or_b64 exec, exec, s[56:57]
	s_nop 0
	v_or_b32_e32 v82, 48, v134
	v_ashrrev_i32_e32 v83, 31, v82
	v_lshlrev_b64 v[84:85], 6, v[82:83]
	v_lshl_add_u64 v[84:85], v[160:161], 0, v[84:85]
	s_nop 1
	v_mov_b32_e32 v84, v204
	v_mov_b32_e32 v85, v205
	v_mov_b32_e32 v86, v206
	v_mov_b32_e32 v87, v207
	v_cmp_lt_i32_e32 vcc, s19, v82
	v_mov_b32_e32 v88, v85
	v_mov_b32_e32 v89, v86
	v_mov_b32_e32 v85, v87
	v_pk_add_f32 v[84:85], v[88:89], v[84:85]
	s_nop 0
	v_add_f32_e32 v84, v84, v85
	ds_bpermute_b32 v85, v144, v84
	s_waitcnt lgkmcnt(0)
	v_add_f32_e32 v88, v84, v85
	ds_bpermute_b32 v89, v145, v88
	s_and_saveexec_b64 s[8:9], vcc
	s_xor_b64 s[8:9], exec, s[8:9]
	s_cbranch_execz .LBB0_1228
	s_cmpk_lt_u32 s63, 0x4400
	s_mov_b64 s[56:57], -1
	s_cbranch_scc1 .LBB0_1224
	s_cmpk_lt_u32 s63, 0x4480
	s_cselect_b64 s[22:23], -1, 0
	s_and_b64 s[22:23], s[22:23], s[0:1]
	v_mov_b64_e32 v[84:85], 0
	s_and_saveexec_b64 s[56:57], s[22:23]
	s_add_i32 s22, s63, 0xffffbc30
	s_lshr_b32 s22, s22, 4
	s_mulk_i32 s22, 0x63
	v_add_u32_e32 v86, s22, v182
	v_mov_b64_e32 v[84:85], s[20:21]
	v_mad_u64_u32 v[84:85], s[22:23], v86, s47, v[84:85]
	s_or_b64 exec, exec, s[56:57]
	s_mov_b64 s[56:57], 0

.LBB0_1243:
	s_or_b64 exec, exec, s[56:57]
	s_add_i32 s58, s63, 0x80
	v_or_b32_e32 v66, s58, v1
	v_ashrrev_i32_e32 v67, 31, v66
	v_lshlrev_b64 v[68:69], 6, v[66:67]
	v_lshl_add_u64 v[68:69], v[160:161], 0, v[68:69]
	s_nop 1
	v_mov_b32_e32 v68, v208
	v_mov_b32_e32 v69, v209
	v_mov_b32_e32 v70, v210
	v_mov_b32_e32 v71, v211
	v_cmp_lt_i32_e32 vcc, s19, v66
	v_mov_b32_e32 v72, v69
	v_mov_b32_e32 v73, v70
	v_mov_b32_e32 v69, v71
	v_pk_add_f32 v[68:69], v[72:73], v[68:69]
	v_mov_b64_e32 v[72:73], 0
	v_add_f32_e32 v68, v68, v69
	ds_bpermute_b32 v69, v144, v68
	s_waitcnt lgkmcnt(0)
	v_add_f32_e32 v70, v68, v69
	ds_bpermute_b32 v71, v145, v70
	v_mov_b64_e32 v[68:69], 0
	s_and_saveexec_b64 s[8:9], vcc
	s_cbranch_execz .LBB0_1252
	s_cmpk_lt_u32 s58, 0x4400
	s_mov_b64 s[56:57], -1
	s_cbranch_scc1 .LBB0_1248
	s_cmpk_lt_u32 s58, 0x4480
	s_cselect_b64 s[22:23], -1, 0
	s_and_b64 s[22:23], s[22:23], s[0:1]
	v_mov_b64_e32 v[68:69], 0
	s_and_saveexec_b64 s[56:57], s[22:23]
	s_add_i32 s22, s63, 0xffffbc80
	s_lshr_b32 s22, s22, 4
	s_mulk_i32 s22, 0x63
	v_add_u32_e32 v72, s22, v182
	v_mov_b64_e32 v[68:69], s[20:21]
	v_mad_u64_u32 v[68:69], s[22:23], v72, s47, v[68:69]
	s_or_b64 exec, exec, s[56:57]
	s_mov_b64 s[56:57], 0

.LBB0_1260:
	s_or_b64 exec, exec, s[56:57]
	s_add_i32 s59, s63, 0x90
	v_or_b32_e32 v50, s59, v1
	v_ashrrev_i32_e32 v51, 31, v50
	v_lshlrev_b64 v[52:53], 6, v[50:51]
	v_lshl_add_u64 v[52:53], v[160:161], 0, v[52:53]
	s_nop 1
	v_mov_b32_e32 v52, v212
	v_mov_b32_e32 v53, v213
	v_mov_b32_e32 v54, v214
	v_mov_b32_e32 v55, v215
	v_cmp_lt_i32_e32 vcc, s19, v50
	v_mov_b32_e32 v56, v53
	v_mov_b32_e32 v57, v54
	v_mov_b32_e32 v53, v55
	v_pk_add_f32 v[52:53], v[56:57], v[52:53]
	v_mov_b64_e32 v[56:57], 0
	v_add_f32_e32 v52, v52, v53
	ds_bpermute_b32 v53, v144, v52
	s_waitcnt lgkmcnt(0)
	v_add_f32_e32 v54, v52, v53
	ds_bpermute_b32 v55, v145, v54
	v_mov_b64_e32 v[52:53], 0
	s_and_saveexec_b64 s[8:9], vcc
	s_cbranch_execz .LBB0_1269
	s_cmpk_lt_u32 s59, 0x4400
	s_mov_b64 s[56:57], -1
	s_cbranch_scc1 .LBB0_1265
	s_cmpk_lt_u32 s59, 0x4480
	s_cselect_b64 s[22:23], -1, 0
	s_and_b64 s[22:23], s[22:23], s[0:1]
	v_mov_b64_e32 v[52:53], 0
	s_and_saveexec_b64 s[56:57], s[22:23]
	s_add_i32 s22, s63, 0xffffbc90
	s_lshr_b32 s22, s22, 4
	s_mulk_i32 s22, 0x63
	v_add_u32_e32 v56, s22, v182
	v_mov_b64_e32 v[52:53], s[20:21]
	v_mad_u64_u32 v[52:53], s[22:23], v56, s47, v[52:53]
	s_or_b64 exec, exec, s[56:57]
	s_mov_b64 s[56:57], 0

.LBB0_1277:
	s_or_b64 exec, exec, s[56:57]
	s_add_i32 s59, s63, 0xa0
	v_or_b32_e32 v34, s59, v1
	v_ashrrev_i32_e32 v35, 31, v34
	v_lshlrev_b64 v[36:37], 6, v[34:35]
	v_lshl_add_u64 v[36:37], v[160:161], 0, v[36:37]
	s_nop 1
	v_mov_b32_e32 v36, v216
	v_mov_b32_e32 v37, v217
	v_mov_b32_e32 v38, v218
	v_mov_b32_e32 v39, v219
	v_cmp_lt_i32_e32 vcc, s19, v34
	v_mov_b32_e32 v40, v37
	v_mov_b32_e32 v41, v38
	v_mov_b32_e32 v37, v39
	v_pk_add_f32 v[36:37], v[40:41], v[36:37]
	v_mov_b64_e32 v[40:41], 0
	v_add_f32_e32 v36, v36, v37
	ds_bpermute_b32 v37, v144, v36
	s_waitcnt lgkmcnt(0)
	v_add_f32_e32 v38, v36, v37
	ds_bpermute_b32 v39, v145, v38
	v_mov_b64_e32 v[36:37], 0
	s_and_saveexec_b64 s[8:9], vcc
	s_cbranch_execz .LBB0_1286
	s_cmpk_lt_u32 s59, 0x4400
	s_mov_b64 s[56:57], -1
	s_cbranch_scc1 .LBB0_1282
	s_cmpk_lt_u32 s59, 0x4480
	s_cselect_b64 s[22:23], -1, 0
	s_and_b64 s[22:23], s[22:23], s[0:1]
	v_mov_b64_e32 v[36:37], 0
	s_and_saveexec_b64 s[56:57], s[22:23]
	s_add_i32 s22, s63, 0xffffbca0
	s_lshr_b32 s22, s22, 4
	s_mulk_i32 s22, 0x63
	v_add_u32_e32 v40, s22, v182
	v_mov_b64_e32 v[36:37], s[20:21]
	v_mad_u64_u32 v[36:37], s[22:23], v40, s47, v[36:37]
	s_or_b64 exec, exec, s[56:57]
	s_mov_b64 s[56:57], 0

.LBB0_1294:
	s_or_b64 exec, exec, s[56:57]
	s_add_i32 s59, s63, 0xb0
	v_or_b32_e32 v18, s59, v1
	v_ashrrev_i32_e32 v19, 31, v18
	v_lshlrev_b64 v[20:21], 6, v[18:19]
	v_lshl_add_u64 v[20:21], v[160:161], 0, v[20:21]
	s_nop 1
	v_mov_b32_e32 v20, v220
	v_mov_b32_e32 v21, v221
	v_mov_b32_e32 v22, v222
	v_mov_b32_e32 v23, v223
	v_cmp_lt_i32_e32 vcc, s19, v18
	v_mov_b32_e32 v24, v21
	v_mov_b32_e32 v25, v22
	v_mov_b32_e32 v21, v23
	v_pk_add_f32 v[20:21], v[24:25], v[20:21]
	s_nop 0
	v_add_f32_e32 v20, v20, v21
	ds_bpermute_b32 v21, v144, v20
	s_waitcnt lgkmcnt(0)
	v_add_f32_e32 v24, v20, v21
	ds_bpermute_b32 v25, v145, v24
	s_and_saveexec_b64 s[8:9], vcc
	s_xor_b64 s[8:9], exec, s[8:9]
	s_cbranch_execz .LBB0_1303
	s_cmpk_lt_u32 s59, 0x4400
	s_mov_b64 s[56:57], -1
	s_cbranch_scc1 .LBB0_1299
	s_cmpk_lt_u32 s59, 0x4480
	s_cselect_b64 s[22:23], -1, 0
	s_and_b64 s[22:23], s[22:23], s[0:1]
	v_mov_b64_e32 v[20:21], 0
	s_and_saveexec_b64 s[56:57], s[22:23]
	s_addk_i32 s63, 0xbcb0
	s_lshr_b32 s22, s63, 4
	s_mulk_i32 s22, 0x63
	v_add_u32_e32 v22, s22, v182
	v_mov_b64_e32 v[20:21], s[20:21]
	v_mad_u64_u32 v[20:21], s[22:23], v22, s47, v[20:21]
	s_or_b64 exec, exec, s[56:57]
	s_mov_b64 s[56:57], 0

.LBB0_2651:
	s_cmp_gt_i32 s6, 7
	s_cselect_b64 s[48:49], -1, 0
	s_lshl_b32 s41, s8, 8
	s_add_i32 s41, s41, s60
	v_or_b32_e32 v154, s41, v1
	v_ashrrev_i32_e32 v155, 31, v154
	v_lshlrev_b64 v[150:151], 6, v[154:155]
	v_lshl_add_u64 v[150:151], v[140:141], 0, v[150:151]
	v_add_co_u32_e32 v212, vcc, 0x2000, v150
	s_nop 1
	v_addc_co_u32_e32 v213, vcc, 0, v151, vcc
	global_load_dwordx4 v[184:187], v[150:151], off offset:1024
	global_load_dwordx4 v[188:191], v[150:151], off offset:2048
	global_load_dwordx4 v[192:195], v[150:151], off offset:3072
	global_load_dwordx4 v[196:199], v[212:213], off
	global_load_dwordx4 v[200:203], v[212:213], off offset:1024
	global_load_dwordx4 v[204:207], v[212:213], off offset:2048
	global_load_dwordx4 v[208:211], v[212:213], off offset:3072
	global_load_dwordx4 v[150:153], v[150:151], off
	v_and_b32_e32 v156, 64, v170
	v_xor_b32_e32 v138, 16, v170
	v_add_u32_e32 v159, 64, v156
	v_cmp_lt_i32_e32 vcc, v138, v159
	v_xor_b32_e32 v158, 32, v170
	s_lshl_b32 s6, s6, 7
	v_cndmask_b32_e32 v138, v170, v138, vcc
	v_lshlrev_b32_e32 v173, 2, v138
	v_cmp_lt_i32_e32 vcc, v158, v159
	s_and_b32 s6, s6, 0x380
	v_or_b32_e32 v172, s6, v166
	s_mov_b64 s[8:9], -1
	s_waitcnt vmcnt(0)
	v_mov_b32_e32 v156, v151
	v_mov_b32_e32 v157, v152
	v_mov_b32_e32 v151, v153
	v_pk_add_f32 v[150:151], v[156:157], v[150:151]
	v_lshlrev_b64 v[156:157], 11, v[154:155]
	v_add_f32_e32 v138, v150, v151
	ds_bpermute_b32 v150, v173, v138
	v_cndmask_b32_e32 v151, v170, v158, vcc
	v_lshlrev_b32_e32 v174, 2, v151
	s_and_b64 vcc, exec, s[48:49]
	s_waitcnt lgkmcnt(0)
	v_add_f32_e32 v150, v138, v150
	ds_bpermute_b32 v151, v174, v150
	v_lshlrev_b32_e32 v138, 1, v172
	v_lshl_add_u64 v[152:153], s[20:21], 0, v[138:139]
	s_waitcnt lgkmcnt(0)
	v_add_f32_e32 v150, v150, v151
	v_fmamk_f32 v150, v150, 0x3a800000, v171
	v_mul_f32_e32 v151, 0x4b800000, v150
	v_cmp_gt_f32_e64 s[6:7], s74, v150
	s_nop 1
	v_cndmask_b32_e64 v150, v150, v151, s[6:7]
	v_rsq_f32_e32 v158, v150
	v_lshl_add_u64 v[150:151], s[62:63], 0, v[138:139]
	v_mul_f32_e32 v155, 0x45800000, v158
	v_cndmask_b32_e64 v158, v158, v155, s[6:7]
	v_pk_mul_f32 v[128:129], v[128:129], v[158:159] op_sel_hi:[1,0]
	v_pk_mul_f32 v[160:161], v[126:127], v[158:159] op_sel_hi:[1,0]
	v_pk_mul_f32 v[124:125], v[124:125], v[158:159] op_sel_hi:[1,0]
	v_pk_mul_f32 v[126:127], v[122:123], v[158:159] op_sel_hi:[1,0]
	v_pk_mul_f32 v[120:121], v[120:121], v[158:159] op_sel_hi:[1,0]
	v_pk_mul_f32 v[162:163], v[118:119], v[158:159] op_sel_hi:[1,0]
	v_pk_mul_f32 v[118:119], v[116:117], v[158:159] op_sel_hi:[1,0]
	v_pk_mul_f32 v[158:159], v[114:115], v[158:159] op_sel_hi:[1,0]
	s_cbranch_vccz .LBB0_2653
	v_mul_f32_e32 v155, 0xbfb8aa3b, v162
	v_mul_f32_e32 v175, 0xbfb8aa3b, v163
	v_exp_f32_e32 v155, v155
	v_exp_f32_e32 v175, v175
	v_cvt_pk_bf16_f32 v114, v160, v161
	v_cvt_pk_bf16_f32 v115, v128, v129
	v_cvt_pk_bf16_f32 v116, v126, v127
	v_cvt_pk_bf16_f32 v117, v124, v125
	v_lshl_add_u64 v[122:123], v[152:153], 0, v[156:157]
	global_store_dwordx4 v[122:123], v[114:117], off
	v_mul_f32_e32 v122, 0xbfb8aa3b, v158
	v_mul_f32_e32 v123, 0xbfb8aa3b, v159
	v_add_f32_e32 v114, 1.0, v155
	v_add_f32_e32 v115, 1.0, v175
	v_mul_f32_e32 v116, 0xbfb8aa3b, v120
	v_mul_f32_e32 v117, 0xbfb8aa3b, v121
	v_mul_f32_e32 v155, 0xbfb8aa3b, v118
	v_mul_f32_e32 v175, 0xbfb8aa3b, v119
	v_exp_f32_e32 v116, v116
	v_exp_f32_e32 v117, v117
	v_exp_f32_e32 v122, v122
	v_exp_f32_e32 v123, v123
	v_exp_f32_e32 v155, v155
	v_exp_f32_e32 v175, v175
	v_add_f32_e32 v116, 1.0, v116
	v_add_f32_e32 v117, 1.0, v117
	v_add_f32_e32 v122, 1.0, v122
	v_add_f32_e32 v123, 1.0, v123
	v_add_f32_e32 v155, 1.0, v155
	v_add_f32_e32 v175, 1.0, v175
	v_rcp_f32_e32 v114, v114
	v_rcp_f32_e32 v115, v115
	v_rcp_f32_e32 v116, v116
	v_rcp_f32_e32 v117, v117
	v_rcp_f32_e32 v122, v122
	v_rcp_f32_e32 v123, v123
	v_rcp_f32_e32 v155, v155
	v_rcp_f32_e32 v175, v175
	v_cvt_pk_bf16_f32 v114, v114, v115
	v_cvt_pk_bf16_f32 v115, v116, v117
	v_cvt_pk_bf16_f32 v116, v122, v123
	v_cvt_pk_bf16_f32 v117, v155, v175
	v_lshl_add_u64 v[122:123], v[150:151], 0, v[156:157]
	global_store_dwordx4 v[122:123], v[114:117], off
	s_mov_b64 s[8:9], 0

.LBB0_2657:
	v_or_b32_e32 v114, 16, v154
	v_ashrrev_i32_e32 v115, 31, v114
	v_lshlrev_b64 v[116:117], 6, v[114:115]
	v_lshl_add_u64 v[116:117], v[140:141], 0, v[116:117]
	s_nop 1
	v_mov_b32_e32 v116, v184
	v_mov_b32_e32 v117, v185
	v_mov_b32_e32 v118, v186
	v_mov_b32_e32 v119, v187
	s_mov_b64 s[50:51], -1
	s_andn2_b64 vcc, exec, s[48:49]
	v_mov_b32_e32 v120, v117
	v_mov_b32_e32 v121, v118
	v_mov_b32_e32 v117, v119
	v_pk_add_f32 v[116:117], v[120:121], v[116:117]
	s_nop 0
	v_add_f32_e32 v116, v116, v117
	ds_bpermute_b32 v117, v173, v116
	s_waitcnt lgkmcnt(0)
	v_add_f32_e32 v116, v116, v117
	ds_bpermute_b32 v117, v174, v116
	s_waitcnt lgkmcnt(0)
	v_add_f32_e32 v116, v116, v117
	v_fmamk_f32 v116, v116, 0x3a800000, v171
	v_mul_f32_e32 v117, 0x4b800000, v116
	v_cmp_gt_f32_e64 s[8:9], s74, v116
	s_nop 1
	v_cndmask_b32_e64 v116, v116, v117, s[8:9]
	v_rsq_f32_e32 v116, v116
	v_cndmask_b32_e64 v117, 0, 1, s[48:49]
	v_cmp_ne_u32_e64 s[6:7], 1, v117
	v_mul_f32_e32 v117, 0x45800000, v116
	v_cndmask_b32_e64 v116, v116, v117, s[8:9]
	v_pk_mul_f32 v[112:113], v[112:113], v[116:117] op_sel_hi:[1,0]
	v_pk_mul_f32 v[118:119], v[110:111], v[116:117] op_sel_hi:[1,0]
	v_pk_mul_f32 v[108:109], v[108:109], v[116:117] op_sel_hi:[1,0]
	v_pk_mul_f32 v[110:111], v[106:107], v[116:117] op_sel_hi:[1,0]
	v_pk_mul_f32 v[104:105], v[104:105], v[116:117] op_sel_hi:[1,0]
	v_pk_mul_f32 v[120:121], v[102:103], v[116:117] op_sel_hi:[1,0]
	v_pk_mul_f32 v[102:103], v[100:101], v[116:117] op_sel_hi:[1,0]
	v_pk_mul_f32 v[116:117], v[98:99], v[116:117] op_sel_hi:[1,0]
	v_lshlrev_b64 v[106:107], 11, v[114:115]
	s_cbranch_vccnz .LBB0_2659
	v_mul_f32_e32 v115, 0xbfb8aa3b, v120
	v_mul_f32_e32 v126, 0xbfb8aa3b, v121
	v_exp_f32_e32 v115, v115
	v_exp_f32_e32 v126, v126
	v_cvt_pk_bf16_f32 v98, v118, v119
	v_cvt_pk_bf16_f32 v99, v112, v113
	v_cvt_pk_bf16_f32 v100, v110, v111
	v_cvt_pk_bf16_f32 v101, v108, v109
	v_lshl_add_u64 v[124:125], v[152:153], 0, v[106:107]
	global_store_dwordx4 v[124:125], v[98:101], off
	v_mul_f32_e32 v124, 0xbfb8aa3b, v117
	v_mul_f32_e32 v125, 0xbfb8aa3b, v102
	v_add_f32_e32 v98, 1.0, v115
	v_add_f32_e32 v99, 1.0, v126
	v_mul_f32_e32 v100, 0xbfb8aa3b, v104
	v_mul_f32_e32 v101, 0xbfb8aa3b, v105
	v_mul_f32_e32 v115, 0xbfb8aa3b, v116
	v_mul_f32_e32 v126, 0xbfb8aa3b, v103
	v_exp_f32_e32 v100, v100
	v_exp_f32_e32 v101, v101
	v_exp_f32_e32 v115, v115
	v_exp_f32_e32 v124, v124
	v_exp_f32_e32 v125, v125
	v_exp_f32_e32 v126, v126
	v_add_f32_e32 v100, 1.0, v100
	v_add_f32_e32 v101, 1.0, v101
	v_add_f32_e32 v115, 1.0, v115
	v_add_f32_e32 v124, 1.0, v124
	v_add_f32_e32 v125, 1.0, v125
	v_add_f32_e32 v126, 1.0, v126
	v_rcp_f32_e32 v98, v98
	v_rcp_f32_e32 v99, v99
	v_rcp_f32_e32 v100, v100
	v_rcp_f32_e32 v101, v101
	v_rcp_f32_e32 v115, v115
	v_rcp_f32_e32 v124, v124
	v_rcp_f32_e32 v125, v125
	v_rcp_f32_e32 v126, v126
	v_cvt_pk_bf16_f32 v98, v98, v99
	v_cvt_pk_bf16_f32 v99, v100, v101
	v_cvt_pk_bf16_f32 v100, v115, v124
	v_cvt_pk_bf16_f32 v101, v125, v126
	v_lshl_add_u64 v[124:125], v[150:151], 0, v[106:107]
	s_mov_b64 s[50:51], 0
	global_store_dwordx4 v[124:125], v[98:101], off

.LBB0_2663:
	v_or_b32_e32 v98, 32, v154
	v_ashrrev_i32_e32 v99, 31, v98
	v_lshlrev_b64 v[100:101], 6, v[98:99]
	v_lshl_add_u64 v[100:101], v[140:141], 0, v[100:101]
	s_nop 1
	v_mov_b32_e32 v100, v188
	v_mov_b32_e32 v101, v189
	v_mov_b32_e32 v102, v190
	v_mov_b32_e32 v103, v191
	s_mov_b64 s[48:49], -1
	s_and_b64 vcc, exec, s[6:7]
	v_mov_b32_e32 v104, v101
	v_mov_b32_e32 v105, v102
	v_mov_b32_e32 v101, v103
	v_pk_add_f32 v[100:101], v[104:105], v[100:101]
	s_nop 0
	v_add_f32_e32 v100, v100, v101
	ds_bpermute_b32 v101, v173, v100
	s_waitcnt lgkmcnt(0)
	v_add_f32_e32 v100, v100, v101
	ds_bpermute_b32 v101, v174, v100
	s_waitcnt lgkmcnt(0)
	v_add_f32_e32 v100, v100, v101
	v_fmamk_f32 v100, v100, 0x3a800000, v171
	v_mul_f32_e32 v101, 0x4b800000, v100
	v_cmp_gt_f32_e64 s[8:9], s74, v100
	s_nop 1
	v_cndmask_b32_e64 v100, v100, v101, s[8:9]
	v_rsq_f32_e32 v100, v100
	s_nop 0
	v_mul_f32_e32 v101, 0x45800000, v100
	v_cndmask_b32_e64 v100, v100, v101, s[8:9]
	v_pk_mul_f32 v[96:97], v[96:97], v[100:101] op_sel_hi:[1,0]
	v_pk_mul_f32 v[102:103], v[94:95], v[100:101] op_sel_hi:[1,0]
	v_pk_mul_f32 v[92:93], v[92:93], v[100:101] op_sel_hi:[1,0]
	v_pk_mul_f32 v[94:95], v[90:91], v[100:101] op_sel_hi:[1,0]
	v_pk_mul_f32 v[88:89], v[88:89], v[100:101] op_sel_hi:[1,0]
	v_pk_mul_f32 v[104:105], v[86:87], v[100:101] op_sel_hi:[1,0]
	v_pk_mul_f32 v[86:87], v[84:85], v[100:101] op_sel_hi:[1,0]
	v_pk_mul_f32 v[100:101], v[82:83], v[100:101] op_sel_hi:[1,0]
	v_lshlrev_b64 v[90:91], 11, v[98:99]
	s_cbranch_vccnz .LBB0_2665
	v_mul_f32_e32 v99, 0xbfb8aa3b, v104
	v_mul_f32_e32 v108, 0xbfb8aa3b, v105
	v_exp_f32_e32 v99, v99
	v_exp_f32_e32 v108, v108
	v_cvt_pk_bf16_f32 v82, v102, v103
	v_cvt_pk_bf16_f32 v83, v96, v97
	v_cvt_pk_bf16_f32 v84, v94, v95
	v_cvt_pk_bf16_f32 v85, v92, v93
	v_lshl_add_u64 v[106:107], v[152:153], 0, v[90:91]
	global_store_dwordx4 v[106:107], v[82:85], off
	v_mul_f32_e32 v106, 0xbfb8aa3b, v101
	v_mul_f32_e32 v107, 0xbfb8aa3b, v86
	v_add_f32_e32 v82, 1.0, v99
	v_add_f32_e32 v83, 1.0, v108
	v_mul_f32_e32 v84, 0xbfb8aa3b, v88
	v_mul_f32_e32 v85, 0xbfb8aa3b, v89
	v_mul_f32_e32 v99, 0xbfb8aa3b, v100
	v_mul_f32_e32 v108, 0xbfb8aa3b, v87
	v_exp_f32_e32 v84, v84
	v_exp_f32_e32 v85, v85
	v_exp_f32_e32 v99, v99
	v_exp_f32_e32 v106, v106
	v_exp_f32_e32 v107, v107
	v_exp_f32_e32 v108, v108
	v_add_f32_e32 v84, 1.0, v84
	v_add_f32_e32 v85, 1.0, v85
	v_add_f32_e32 v99, 1.0, v99
	v_add_f32_e32 v106, 1.0, v106
	v_add_f32_e32 v107, 1.0, v107
	v_add_f32_e32 v108, 1.0, v108
	v_rcp_f32_e32 v82, v82
	v_rcp_f32_e32 v83, v83
	v_rcp_f32_e32 v84, v84
	v_rcp_f32_e32 v85, v85
	v_rcp_f32_e32 v99, v99
	v_rcp_f32_e32 v106, v106
	v_rcp_f32_e32 v107, v107
	v_rcp_f32_e32 v108, v108
	v_cvt_pk_bf16_f32 v82, v82, v83
	v_cvt_pk_bf16_f32 v83, v84, v85
	v_cvt_pk_bf16_f32 v84, v99, v106
	v_cvt_pk_bf16_f32 v85, v107, v108
	v_lshl_add_u64 v[106:107], v[150:151], 0, v[90:91]
	s_mov_b64 s[48:49], 0
	global_store_dwordx4 v[106:107], v[82:85], off

.LBB0_2669:
	v_or_b32_e32 v82, 48, v154
	v_ashrrev_i32_e32 v83, 31, v82
	v_lshlrev_b64 v[84:85], 6, v[82:83]
	v_lshl_add_u64 v[84:85], v[140:141], 0, v[84:85]
	s_nop 1
	v_mov_b32_e32 v84, v192
	v_mov_b32_e32 v85, v193
	v_mov_b32_e32 v86, v194
	v_mov_b32_e32 v87, v195
	s_mov_b64 s[48:49], -1
	s_and_b64 vcc, exec, s[6:7]
	v_mov_b32_e32 v88, v85
	v_mov_b32_e32 v89, v86
	v_mov_b32_e32 v85, v87
	v_pk_add_f32 v[84:85], v[88:89], v[84:85]
	s_nop 0
	v_add_f32_e32 v84, v84, v85
	ds_bpermute_b32 v85, v173, v84
	s_waitcnt lgkmcnt(0)
	v_add_f32_e32 v84, v84, v85
	ds_bpermute_b32 v85, v174, v84
	s_waitcnt lgkmcnt(0)
	v_add_f32_e32 v84, v84, v85
	v_fmamk_f32 v84, v84, 0x3a800000, v171
	v_mul_f32_e32 v85, 0x4b800000, v84
	v_cmp_gt_f32_e64 s[8:9], s74, v84
	s_nop 1
	v_cndmask_b32_e64 v84, v84, v85, s[8:9]
	v_rsq_f32_e32 v84, v84
	s_nop 0
	v_mul_f32_e32 v85, 0x45800000, v84
	v_cndmask_b32_e64 v84, v84, v85, s[8:9]
	v_pk_mul_f32 v[80:81], v[80:81], v[84:85] op_sel_hi:[1,0]
	v_pk_mul_f32 v[86:87], v[78:79], v[84:85] op_sel_hi:[1,0]
	v_pk_mul_f32 v[76:77], v[76:77], v[84:85] op_sel_hi:[1,0]
	v_pk_mul_f32 v[78:79], v[74:75], v[84:85] op_sel_hi:[1,0]
	v_pk_mul_f32 v[72:73], v[72:73], v[84:85] op_sel_hi:[1,0]
	v_pk_mul_f32 v[88:89], v[70:71], v[84:85] op_sel_hi:[1,0]
	v_pk_mul_f32 v[70:71], v[68:69], v[84:85] op_sel_hi:[1,0]
	v_pk_mul_f32 v[84:85], v[66:67], v[84:85] op_sel_hi:[1,0]
	v_lshlrev_b64 v[74:75], 11, v[82:83]
	s_cbranch_vccnz .LBB0_2671
	v_mul_f32_e32 v83, 0xbfb8aa3b, v88
	v_mul_f32_e32 v92, 0xbfb8aa3b, v89
	v_exp_f32_e32 v83, v83
	v_exp_f32_e32 v92, v92
	v_cvt_pk_bf16_f32 v66, v86, v87
	v_cvt_pk_bf16_f32 v67, v80, v81
	v_cvt_pk_bf16_f32 v68, v78, v79
	v_cvt_pk_bf16_f32 v69, v76, v77
	v_lshl_add_u64 v[90:91], v[152:153], 0, v[74:75]
	global_store_dwordx4 v[90:91], v[66:69], off
	v_mul_f32_e32 v90, 0xbfb8aa3b, v85
	v_mul_f32_e32 v91, 0xbfb8aa3b, v70
	v_add_f32_e32 v66, 1.0, v83
	v_add_f32_e32 v67, 1.0, v92
	v_mul_f32_e32 v68, 0xbfb8aa3b, v72
	v_mul_f32_e32 v69, 0xbfb8aa3b, v73
	v_mul_f32_e32 v83, 0xbfb8aa3b, v84
	v_mul_f32_e32 v92, 0xbfb8aa3b, v71
	v_exp_f32_e32 v68, v68
	v_exp_f32_e32 v69, v69
	v_exp_f32_e32 v83, v83
	v_exp_f32_e32 v90, v90
	v_exp_f32_e32 v91, v91
	v_exp_f32_e32 v92, v92
	v_add_f32_e32 v68, 1.0, v68
	v_add_f32_e32 v69, 1.0, v69
	v_add_f32_e32 v83, 1.0, v83
	v_add_f32_e32 v90, 1.0, v90
	v_add_f32_e32 v91, 1.0, v91
	v_add_f32_e32 v92, 1.0, v92
	v_rcp_f32_e32 v66, v66
	v_rcp_f32_e32 v67, v67
	v_rcp_f32_e32 v68, v68
	v_rcp_f32_e32 v69, v69
	v_rcp_f32_e32 v83, v83
	v_rcp_f32_e32 v90, v90
	v_rcp_f32_e32 v91, v91
	v_rcp_f32_e32 v92, v92
	v_cvt_pk_bf16_f32 v66, v66, v67
	v_cvt_pk_bf16_f32 v67, v68, v69
	v_cvt_pk_bf16_f32 v68, v83, v90
	v_cvt_pk_bf16_f32 v69, v91, v92
	v_lshl_add_u64 v[90:91], v[150:151], 0, v[74:75]
	s_mov_b64 s[48:49], 0
	global_store_dwordx4 v[90:91], v[66:69], off

.LBB0_2679:
	s_add_i32 s43, s41, 0x80
	v_or_b32_e32 v66, s43, v1
	v_ashrrev_i32_e32 v67, 31, v66
	v_lshlrev_b64 v[68:69], 6, v[66:67]
	v_lshl_add_u64 v[68:69], v[140:141], 0, v[68:69]
	s_nop 1
	v_mov_b32_e32 v68, v196
	v_mov_b32_e32 v69, v197
	v_mov_b32_e32 v70, v198
	v_mov_b32_e32 v71, v199
	s_mov_b64 s[48:49], -1
	s_and_b64 vcc, exec, s[6:7]
	v_mov_b32_e32 v72, v69
	v_mov_b32_e32 v73, v70
	v_mov_b32_e32 v69, v71
	v_pk_add_f32 v[68:69], v[72:73], v[68:69]
	s_nop 0
	v_add_f32_e32 v68, v68, v69
	ds_bpermute_b32 v69, v173, v68
	s_waitcnt lgkmcnt(0)
	v_add_f32_e32 v68, v68, v69
	ds_bpermute_b32 v69, v174, v68
	s_waitcnt lgkmcnt(0)
	v_add_f32_e32 v68, v68, v69
	v_fmamk_f32 v68, v68, 0x3a800000, v171
	v_mul_f32_e32 v69, 0x4b800000, v68
	v_cmp_gt_f32_e64 s[8:9], s74, v68
	s_nop 1
	v_cndmask_b32_e64 v68, v68, v69, s[8:9]
	v_rsq_f32_e32 v68, v68
	s_nop 0
	v_mul_f32_e32 v69, 0x45800000, v68
	v_cndmask_b32_e64 v68, v68, v69, s[8:9]
	v_pk_mul_f32 v[64:65], v[64:65], v[68:69] op_sel_hi:[1,0]
	v_pk_mul_f32 v[70:71], v[62:63], v[68:69] op_sel_hi:[1,0]
	v_pk_mul_f32 v[60:61], v[60:61], v[68:69] op_sel_hi:[1,0]
	v_pk_mul_f32 v[62:63], v[58:59], v[68:69] op_sel_hi:[1,0]
	v_pk_mul_f32 v[56:57], v[56:57], v[68:69] op_sel_hi:[1,0]
	v_pk_mul_f32 v[72:73], v[54:55], v[68:69] op_sel_hi:[1,0]
	v_pk_mul_f32 v[54:55], v[52:53], v[68:69] op_sel_hi:[1,0]
	v_pk_mul_f32 v[68:69], v[50:51], v[68:69] op_sel_hi:[1,0]
	v_lshlrev_b64 v[58:59], 11, v[66:67]
	s_cbranch_vccnz .LBB0_2681
	v_mul_f32_e32 v67, 0xbfb8aa3b, v72
	v_mul_f32_e32 v76, 0xbfb8aa3b, v73
	v_exp_f32_e32 v67, v67
	v_exp_f32_e32 v76, v76
	v_cvt_pk_bf16_f32 v50, v70, v71
	v_cvt_pk_bf16_f32 v51, v64, v65
	v_cvt_pk_bf16_f32 v52, v62, v63
	v_cvt_pk_bf16_f32 v53, v60, v61
	v_lshl_add_u64 v[74:75], v[152:153], 0, v[58:59]
	global_store_dwordx4 v[74:75], v[50:53], off
	v_mul_f32_e32 v74, 0xbfb8aa3b, v69
	v_mul_f32_e32 v75, 0xbfb8aa3b, v54
	v_add_f32_e32 v50, 1.0, v67
	v_add_f32_e32 v51, 1.0, v76
	v_mul_f32_e32 v52, 0xbfb8aa3b, v56
	v_mul_f32_e32 v53, 0xbfb8aa3b, v57
	v_mul_f32_e32 v67, 0xbfb8aa3b, v68
	v_mul_f32_e32 v76, 0xbfb8aa3b, v55
	v_exp_f32_e32 v52, v52
	v_exp_f32_e32 v53, v53
	v_exp_f32_e32 v67, v67
	v_exp_f32_e32 v74, v74
	v_exp_f32_e32 v75, v75
	v_exp_f32_e32 v76, v76
	v_add_f32_e32 v52, 1.0, v52
	v_add_f32_e32 v53, 1.0, v53
	v_add_f32_e32 v67, 1.0, v67
	v_add_f32_e32 v74, 1.0, v74
	v_add_f32_e32 v75, 1.0, v75
	v_add_f32_e32 v76, 1.0, v76
	v_rcp_f32_e32 v50, v50
	v_rcp_f32_e32 v51, v51
	v_rcp_f32_e32 v52, v52
	v_rcp_f32_e32 v53, v53
	v_rcp_f32_e32 v67, v67
	v_rcp_f32_e32 v74, v74
	v_rcp_f32_e32 v75, v75
	v_rcp_f32_e32 v76, v76
	v_cvt_pk_bf16_f32 v50, v50, v51
	v_cvt_pk_bf16_f32 v51, v52, v53
	v_cvt_pk_bf16_f32 v52, v67, v74
	v_cvt_pk_bf16_f32 v53, v75, v76
	v_lshl_add_u64 v[74:75], v[150:151], 0, v[58:59]
	s_mov_b64 s[48:49], 0
	global_store_dwordx4 v[74:75], v[50:53], off

.LBB0_2685:
	s_add_i32 s50, s41, 0x90
	v_or_b32_e32 v50, s50, v1
	v_ashrrev_i32_e32 v51, 31, v50
	v_lshlrev_b64 v[52:53], 6, v[50:51]
	v_lshl_add_u64 v[52:53], v[140:141], 0, v[52:53]
	s_nop 1
	v_mov_b32_e32 v52, v200
	v_mov_b32_e32 v53, v201
	v_mov_b32_e32 v54, v202
	v_mov_b32_e32 v55, v203
	s_mov_b64 s[48:49], -1
	s_and_b64 vcc, exec, s[6:7]
	v_mov_b32_e32 v56, v53
	v_mov_b32_e32 v57, v54
	v_mov_b32_e32 v53, v55
	v_pk_add_f32 v[52:53], v[56:57], v[52:53]
	s_nop 0
	v_add_f32_e32 v52, v52, v53
	ds_bpermute_b32 v53, v173, v52
	s_waitcnt lgkmcnt(0)
	v_add_f32_e32 v52, v52, v53
	ds_bpermute_b32 v53, v174, v52
	s_waitcnt lgkmcnt(0)
	v_add_f32_e32 v52, v52, v53
	v_fmamk_f32 v52, v52, 0x3a800000, v171
	v_mul_f32_e32 v53, 0x4b800000, v52
	v_cmp_gt_f32_e64 s[8:9], s74, v52
	s_nop 1
	v_cndmask_b32_e64 v52, v52, v53, s[8:9]
	v_rsq_f32_e32 v52, v52
	s_nop 0
	v_mul_f32_e32 v53, 0x45800000, v52
	v_cndmask_b32_e64 v52, v52, v53, s[8:9]
	v_pk_mul_f32 v[48:49], v[48:49], v[52:53] op_sel_hi:[1,0]
	v_pk_mul_f32 v[54:55], v[46:47], v[52:53] op_sel_hi:[1,0]
	v_pk_mul_f32 v[44:45], v[44:45], v[52:53] op_sel_hi:[1,0]
	v_pk_mul_f32 v[46:47], v[42:43], v[52:53] op_sel_hi:[1,0]
	v_pk_mul_f32 v[40:41], v[40:41], v[52:53] op_sel_hi:[1,0]
	v_pk_mul_f32 v[56:57], v[38:39], v[52:53] op_sel_hi:[1,0]
	v_pk_mul_f32 v[38:39], v[36:37], v[52:53] op_sel_hi:[1,0]
	v_pk_mul_f32 v[52:53], v[34:35], v[52:53] op_sel_hi:[1,0]
	v_lshlrev_b64 v[42:43], 11, v[50:51]
	s_cbranch_vccnz .LBB0_2687
	v_mul_f32_e32 v51, 0xbfb8aa3b, v56
	v_mul_f32_e32 v60, 0xbfb8aa3b, v57
	v_exp_f32_e32 v51, v51
	v_exp_f32_e32 v60, v60
	v_cvt_pk_bf16_f32 v34, v54, v55
	v_cvt_pk_bf16_f32 v35, v48, v49
	v_cvt_pk_bf16_f32 v36, v46, v47
	v_cvt_pk_bf16_f32 v37, v44, v45
	v_lshl_add_u64 v[58:59], v[152:153], 0, v[42:43]
	global_store_dwordx4 v[58:59], v[34:37], off
	v_mul_f32_e32 v58, 0xbfb8aa3b, v53
	v_mul_f32_e32 v59, 0xbfb8aa3b, v38
	v_add_f32_e32 v34, 1.0, v51
	v_add_f32_e32 v35, 1.0, v60
	v_mul_f32_e32 v36, 0xbfb8aa3b, v40
	v_mul_f32_e32 v37, 0xbfb8aa3b, v41
	v_mul_f32_e32 v51, 0xbfb8aa3b, v52
	v_mul_f32_e32 v60, 0xbfb8aa3b, v39
	v_exp_f32_e32 v36, v36
	v_exp_f32_e32 v37, v37
	v_exp_f32_e32 v51, v51
	v_exp_f32_e32 v58, v58
	v_exp_f32_e32 v59, v59
	v_exp_f32_e32 v60, v60
	v_add_f32_e32 v36, 1.0, v36
	v_add_f32_e32 v37, 1.0, v37
	v_add_f32_e32 v51, 1.0, v51
	v_add_f32_e32 v58, 1.0, v58
	v_add_f32_e32 v59, 1.0, v59
	v_add_f32_e32 v60, 1.0, v60
	v_rcp_f32_e32 v34, v34
	v_rcp_f32_e32 v35, v35
	v_rcp_f32_e32 v36, v36
	v_rcp_f32_e32 v37, v37
	v_rcp_f32_e32 v51, v51
	v_rcp_f32_e32 v58, v58
	v_rcp_f32_e32 v59, v59
	v_rcp_f32_e32 v60, v60
	v_cvt_pk_bf16_f32 v34, v34, v35
	v_cvt_pk_bf16_f32 v35, v36, v37
	v_cvt_pk_bf16_f32 v36, v51, v58
	v_cvt_pk_bf16_f32 v37, v59, v60
	v_lshl_add_u64 v[58:59], v[150:151], 0, v[42:43]
	s_mov_b64 s[48:49], 0
	global_store_dwordx4 v[58:59], v[34:37], off

.LBB0_2691:
	s_add_i32 s50, s41, 0xa0
	v_or_b32_e32 v34, s50, v1
	v_ashrrev_i32_e32 v35, 31, v34
	v_lshlrev_b64 v[36:37], 6, v[34:35]
	v_lshl_add_u64 v[36:37], v[140:141], 0, v[36:37]
	s_nop 1
	v_mov_b32_e32 v36, v204
	v_mov_b32_e32 v37, v205
	v_mov_b32_e32 v38, v206
	v_mov_b32_e32 v39, v207
	s_mov_b64 s[48:49], -1
	s_and_b64 vcc, exec, s[6:7]
	v_mov_b32_e32 v40, v37
	v_mov_b32_e32 v41, v38
	v_mov_b32_e32 v37, v39
	v_pk_add_f32 v[36:37], v[40:41], v[36:37]
	s_nop 0
	v_add_f32_e32 v36, v36, v37
	ds_bpermute_b32 v37, v173, v36
	s_waitcnt lgkmcnt(0)
	v_add_f32_e32 v36, v36, v37
	ds_bpermute_b32 v37, v174, v36
	s_waitcnt lgkmcnt(0)
	v_add_f32_e32 v36, v36, v37
	v_fmamk_f32 v36, v36, 0x3a800000, v171
	v_mul_f32_e32 v37, 0x4b800000, v36
	v_cmp_gt_f32_e64 s[8:9], s74, v36
	s_nop 1
	v_cndmask_b32_e64 v36, v36, v37, s[8:9]
	v_rsq_f32_e32 v36, v36
	s_nop 0
	v_mul_f32_e32 v37, 0x45800000, v36
	v_cndmask_b32_e64 v36, v36, v37, s[8:9]
	v_pk_mul_f32 v[32:33], v[32:33], v[36:37] op_sel_hi:[1,0]
	v_pk_mul_f32 v[38:39], v[30:31], v[36:37] op_sel_hi:[1,0]
	v_pk_mul_f32 v[28:29], v[28:29], v[36:37] op_sel_hi:[1,0]
	v_pk_mul_f32 v[30:31], v[26:27], v[36:37] op_sel_hi:[1,0]
	v_pk_mul_f32 v[24:25], v[24:25], v[36:37] op_sel_hi:[1,0]
	v_pk_mul_f32 v[40:41], v[22:23], v[36:37] op_sel_hi:[1,0]
	v_pk_mul_f32 v[22:23], v[20:21], v[36:37] op_sel_hi:[1,0]
	v_pk_mul_f32 v[36:37], v[18:19], v[36:37] op_sel_hi:[1,0]
	v_lshlrev_b64 v[26:27], 11, v[34:35]
	s_cbranch_vccnz .LBB0_2693
	v_mul_f32_e32 v35, 0xbfb8aa3b, v40
	v_mul_f32_e32 v44, 0xbfb8aa3b, v41
	v_exp_f32_e32 v35, v35
	v_exp_f32_e32 v44, v44
	v_cvt_pk_bf16_f32 v18, v38, v39
	v_cvt_pk_bf16_f32 v19, v32, v33
	v_cvt_pk_bf16_f32 v20, v30, v31
	v_cvt_pk_bf16_f32 v21, v28, v29
	v_lshl_add_u64 v[42:43], v[152:153], 0, v[26:27]
	global_store_dwordx4 v[42:43], v[18:21], off
	v_mul_f32_e32 v42, 0xbfb8aa3b, v37
	v_mul_f32_e32 v43, 0xbfb8aa3b, v22
	v_add_f32_e32 v18, 1.0, v35
	v_add_f32_e32 v19, 1.0, v44
	v_mul_f32_e32 v20, 0xbfb8aa3b, v24
	v_mul_f32_e32 v21, 0xbfb8aa3b, v25
	v_mul_f32_e32 v35, 0xbfb8aa3b, v36
	v_mul_f32_e32 v44, 0xbfb8aa3b, v23
	v_exp_f32_e32 v20, v20
	v_exp_f32_e32 v21, v21
	v_exp_f32_e32 v35, v35
	v_exp_f32_e32 v42, v42
	v_exp_f32_e32 v43, v43
	v_exp_f32_e32 v44, v44
	v_add_f32_e32 v20, 1.0, v20
	v_add_f32_e32 v21, 1.0, v21
	v_add_f32_e32 v35, 1.0, v35
	v_add_f32_e32 v42, 1.0, v42
	v_add_f32_e32 v43, 1.0, v43
	v_add_f32_e32 v44, 1.0, v44
	v_rcp_f32_e32 v18, v18
	v_rcp_f32_e32 v19, v19
	v_rcp_f32_e32 v20, v20
	v_rcp_f32_e32 v21, v21
	v_rcp_f32_e32 v35, v35
	v_rcp_f32_e32 v42, v42
	v_rcp_f32_e32 v43, v43
	v_rcp_f32_e32 v44, v44
	v_cvt_pk_bf16_f32 v18, v18, v19
	v_cvt_pk_bf16_f32 v19, v20, v21
	v_cvt_pk_bf16_f32 v20, v35, v42
	v_cvt_pk_bf16_f32 v21, v43, v44
	v_lshl_add_u64 v[42:43], v[150:151], 0, v[26:27]
	s_mov_b64 s[48:49], 0
	global_store_dwordx4 v[42:43], v[18:21], off

.LBB0_2697:
	s_addk_i32 s41, 0xb0
	v_or_b32_e32 v18, s41, v1
	v_ashrrev_i32_e32 v19, 31, v18
	v_lshlrev_b64 v[20:21], 6, v[18:19]
	v_lshl_add_u64 v[20:21], v[140:141], 0, v[20:21]
	s_nop 1
	v_mov_b32_e32 v20, v208
	v_mov_b32_e32 v21, v209
	v_mov_b32_e32 v22, v210
	v_mov_b32_e32 v23, v211
	s_mov_b64 s[48:49], -1
	s_and_b64 vcc, exec, s[6:7]
	v_mov_b32_e32 v24, v21
	v_mov_b32_e32 v25, v22
	v_mov_b32_e32 v21, v23
	v_pk_add_f32 v[20:21], v[24:25], v[20:21]
	s_nop 0
	v_add_f32_e32 v20, v20, v21
	ds_bpermute_b32 v21, v173, v20
	s_waitcnt lgkmcnt(0)
	v_add_f32_e32 v20, v20, v21
	ds_bpermute_b32 v21, v174, v20
	s_waitcnt lgkmcnt(0)
	v_add_f32_e32 v20, v20, v21
	v_fmamk_f32 v20, v20, 0x3a800000, v171
	v_mul_f32_e32 v21, 0x4b800000, v20
	v_cmp_gt_f32_e64 s[8:9], s74, v20
	s_nop 1
	v_cndmask_b32_e64 v20, v20, v21, s[8:9]
	v_rsq_f32_e32 v20, v20
	s_nop 0
	v_mul_f32_e32 v21, 0x45800000, v20
	v_cndmask_b32_e64 v20, v20, v21, s[8:9]
	v_pk_mul_f32 v[16:17], v[16:17], v[20:21] op_sel_hi:[1,0]
	v_pk_mul_f32 v[22:23], v[14:15], v[20:21] op_sel_hi:[1,0]
	v_pk_mul_f32 v[12:13], v[12:13], v[20:21] op_sel_hi:[1,0]
	v_pk_mul_f32 v[14:15], v[10:11], v[20:21] op_sel_hi:[1,0]
	v_pk_mul_f32 v[8:9], v[8:9], v[20:21] op_sel_hi:[1,0]
	v_pk_mul_f32 v[24:25], v[6:7], v[20:21] op_sel_hi:[1,0]
	v_pk_mul_f32 v[6:7], v[4:5], v[20:21] op_sel_hi:[1,0]
	v_pk_mul_f32 v[20:21], v[2:3], v[20:21] op_sel_hi:[1,0]
	v_lshlrev_b64 v[10:11], 11, v[18:19]
	s_cbranch_vccz .LBB0_2700
	s_andn2_b64 vcc, exec, s[48:49]
	s_cbranch_vccz .LBB0_2701
